# NSA select unit: the per-element bias-table LDS lookups (59 of 64 per head) issued in batches of 11-12 with counted lgkmcnt waits, and the psum LDS read-add-write chain done in batches of 16, instead
# speedup vs baseline: 1.0008x; 1.0008x over previous
.LBB0_851:
	s_addk_i32 s33, 0x210
	s_mov_b64 s[70:71], 0x100
	s_cmpk_eq_i32 s33, 0x630
	v_lshl_add_u64 v[110:111], v[110:111], 0, s[70:71]
	s_cbranch_scc1 .LBB0_980
.LBB0_852:
	global_load_dwordx4 v[22:25], v[110:111], off offset:-128
	global_load_dwordx4 v[32:35], v[110:111], off offset:-96
	global_load_dwordx4 v[44:47], v[110:111], off offset:-64
	global_load_dwordx4 v[16:19], v[110:111], off offset:-32
	global_load_dwordx4 v[12:15], v[110:111], off
	global_load_dwordx4 v[8:11], v[110:111], off offset:32
	global_load_dwordx4 v[4:7], v[110:111], off offset:64
	global_load_dwordx4 v[0:3], v[110:111], off offset:96
	s_mov_b32 s72, 0xf800000
	s_cmp_lg_u32 s33, 0
	s_waitcnt vmcnt(7)
	v_lshlrev_b32_e32 v20, 16, v22
	v_and_b32_e32 v21, 0xffff0000, v22
	v_lshlrev_b32_e32 v22, 16, v23
	v_and_b32_e32 v23, 0xffff0000, v23
	v_mul_f32_e32 v26, v21, v21
	v_mul_f32_e32 v27, v23, v23
	v_fmac_f32_e32 v26, v20, v20
	v_fmac_f32_e32 v27, v22, v22
	v_add_f32_e32 v28, v26, v27
	v_and_b32_e32 v27, 0xffff0000, v24
	v_lshlrev_b32_e32 v26, 16, v24
	v_mul_f32_e32 v24, v27, v27
	v_and_b32_e32 v31, 0xffff0000, v25
	v_fmac_f32_e32 v24, v26, v26
	v_lshlrev_b32_e32 v30, 16, v25
	v_mul_f32_e32 v25, v31, v31
	v_add_f32_e32 v24, v24, v28
	v_fmac_f32_e32 v25, v30, v30
	v_add_f32_e32 v28, v25, v24
	s_waitcnt vmcnt(6)
	v_and_b32_e32 v25, 0xffff0000, v32
	v_lshlrev_b32_e32 v24, 16, v32
	v_mul_f32_e32 v29, v25, v25
	v_fmac_f32_e32 v29, v24, v24
	v_add_f32_e32 v32, v29, v28
	v_and_b32_e32 v29, 0xffff0000, v33
	v_lshlrev_b32_e32 v28, 16, v33
	v_mul_f32_e32 v33, v29, v29
	v_fmac_f32_e32 v33, v28, v28
	v_and_b32_e32 v37, 0xffff0000, v34
	v_add_f32_e32 v32, v33, v32
	v_lshlrev_b32_e32 v36, 16, v34
	v_mul_f32_e32 v33, v37, v37
	v_fmac_f32_e32 v33, v36, v36
	v_and_b32_e32 v39, 0xffff0000, v35
	v_add_f32_e32 v32, v33, v32
	v_lshlrev_b32_e32 v38, 16, v35
	v_mul_f32_e32 v33, v39, v39
	v_fmac_f32_e32 v33, v38, v38
	s_waitcnt vmcnt(5)
	v_and_b32_e32 v41, 0xffff0000, v44
	v_add_f32_e32 v32, v33, v32
	v_lshlrev_b32_e32 v40, 16, v44
	v_mul_f32_e32 v33, v41, v41
	v_fmac_f32_e32 v33, v40, v40
	v_and_b32_e32 v43, 0xffff0000, v45
	v_add_f32_e32 v32, v33, v32
	v_lshlrev_b32_e32 v42, 16, v45
	v_mul_f32_e32 v33, v43, v43
	v_fmac_f32_e32 v33, v42, v42
	v_lshlrev_b32_e32 v45, 16, v46
	v_and_b32_e32 v46, 0xffff0000, v46
	v_add_f32_e32 v32, v33, v32
	v_mul_f32_e32 v33, v46, v46
	v_fmac_f32_e32 v33, v45, v45
	v_and_b32_e32 v49, 0xffff0000, v47
	v_add_f32_e32 v32, v33, v32
	v_lshlrev_b32_e32 v48, 16, v47
	v_mul_f32_e32 v33, v49, v49
	v_fmac_f32_e32 v33, v48, v48
	s_waitcnt vmcnt(4)
	v_lshlrev_b32_e32 v44, 16, v16
	v_and_b32_e32 v16, 0xffff0000, v16
	v_add_f32_e32 v32, v33, v32
	v_mul_f32_e32 v33, v16, v16
	v_fmac_f32_e32 v33, v44, v44
	v_lshlrev_b32_e32 v47, 16, v17
	v_and_b32_e32 v17, 0xffff0000, v17
	v_add_f32_e32 v32, v33, v32
	v_mul_f32_e32 v33, v17, v17
	v_and_b32_e32 v51, 0xffff0000, v18
	v_fmac_f32_e32 v33, v47, v47
	v_lshlrev_b32_e32 v50, 16, v18
	v_mul_f32_e32 v18, v51, v51
	v_and_b32_e32 v53, 0xffff0000, v19
	v_add_f32_e32 v32, v33, v32
	v_fmac_f32_e32 v18, v50, v50
	v_lshlrev_b32_e32 v52, 16, v19
	v_mul_f32_e32 v19, v53, v53
	v_add_f32_e32 v18, v18, v32
	v_fmac_f32_e32 v19, v52, v52
	v_add_f32_e32 v19, v19, v18
	s_waitcnt vmcnt(3)
	v_lshlrev_b32_e32 v18, 16, v12
	v_and_b32_e32 v12, 0xffff0000, v12
	v_mul_f32_e32 v32, v12, v12
	v_fmac_f32_e32 v32, v18, v18
	v_add_f32_e32 v32, v32, v19
	v_lshlrev_b32_e32 v19, 16, v13
	v_and_b32_e32 v13, 0xffff0000, v13
	v_mul_f32_e32 v33, v13, v13
	v_fmac_f32_e32 v33, v19, v19
	v_lshlrev_b32_e32 v54, 16, v14
	v_and_b32_e32 v14, 0xffff0000, v14
	v_add_f32_e32 v32, v33, v32
	v_mul_f32_e32 v33, v14, v14
	v_fmac_f32_e32 v33, v54, v54
	v_lshlrev_b32_e32 v55, 16, v15
	v_and_b32_e32 v15, 0xffff0000, v15
	v_add_f32_e32 v32, v33, v32
	v_mul_f32_e32 v33, v15, v15
	v_fmac_f32_e32 v33, v55, v55
	s_waitcnt vmcnt(2)
	v_lshlrev_b32_e32 v56, 16, v8
	v_and_b32_e32 v8, 0xffff0000, v8
	v_add_f32_e32 v32, v33, v32
	v_mul_f32_e32 v33, v8, v8
	v_fmac_f32_e32 v33, v56, v56
	v_lshlrev_b32_e32 v57, 16, v9
	v_and_b32_e32 v9, 0xffff0000, v9
	v_add_f32_e32 v32, v33, v32
	v_mul_f32_e32 v33, v9, v9
	v_fmac_f32_e32 v33, v57, v57
	v_lshlrev_b32_e32 v58, 16, v10
	v_and_b32_e32 v10, 0xffff0000, v10
	v_add_f32_e32 v32, v33, v32
	v_mul_f32_e32 v33, v10, v10
	v_fmac_f32_e32 v33, v58, v58
	v_lshlrev_b32_e32 v59, 16, v11
	v_and_b32_e32 v11, 0xffff0000, v11
	v_add_f32_e32 v32, v33, v32
	v_mul_f32_e32 v33, v11, v11
	s_waitcnt vmcnt(1)
	v_and_b32_e32 v192, 0xffff0000, v4
	v_fmac_f32_e32 v33, v59, v59
	v_lshlrev_b32_e32 v191, 16, v4
	v_mul_f32_e32 v4, v192, v192
	v_and_b32_e32 v194, 0xffff0000, v5
	v_add_f32_e32 v32, v33, v32
	v_fmac_f32_e32 v4, v191, v191
	v_lshlrev_b32_e32 v193, 16, v5
	v_mul_f32_e32 v5, v194, v194
	v_add_f32_e32 v4, v4, v32
	v_fmac_f32_e32 v5, v193, v193
	v_and_b32_e32 v196, 0xffff0000, v6
	v_add_f32_e32 v4, v5, v4
	v_lshlrev_b32_e32 v195, 16, v6
	v_mul_f32_e32 v5, v196, v196
	v_fmac_f32_e32 v5, v195, v195
	v_and_b32_e32 v198, 0xffff0000, v7
	v_add_f32_e32 v4, v5, v4
	v_lshlrev_b32_e32 v197, 16, v7
	v_mul_f32_e32 v5, v198, v198
	s_waitcnt vmcnt(0)
	v_and_b32_e32 v200, 0xffff0000, v0
	v_fmac_f32_e32 v5, v197, v197
	v_lshlrev_b32_e32 v199, 16, v0
	v_mul_f32_e32 v0, v200, v200
	v_and_b32_e32 v202, 0xffff0000, v1
	v_add_f32_e32 v4, v5, v4
	v_fmac_f32_e32 v0, v199, v199
	v_lshlrev_b32_e32 v201, 16, v1
	v_mul_f32_e32 v1, v202, v202
	v_add_f32_e32 v0, v0, v4
	v_fmac_f32_e32 v1, v201, v201
	v_and_b32_e32 v204, 0xffff0000, v2
	v_add_f32_e32 v0, v1, v0
	v_lshlrev_b32_e32 v203, 16, v2
	v_mul_f32_e32 v1, v204, v204
	v_fmac_f32_e32 v1, v203, v203
	v_and_b32_e32 v214, 0xffff0000, v3
	v_add_f32_e32 v0, v1, v0
	v_lshlrev_b32_e32 v205, 16, v3
	v_mul_f32_e32 v1, v214, v214
	v_fmac_f32_e32 v1, v205, v205
	v_add_f32_e32 v0, v1, v0
	v_mov_b32_e32 v1, v0
	s_nop 1
	v_permlane32_swap_b32_e32 v0, v1
	v_add_f32_e32 v0, v0, v1
	v_fmamk_f32 v0, v0, 0x3c000000, v206
	v_cmp_gt_f32_e32 vcc, s72, v0
	v_mul_f32_e32 v1, 0x4f800000, v0
	s_nop 0
	v_cndmask_b32_e32 v0, v0, v1, vcc
	v_sqrt_f32_e32 v1, v0
	s_nop 0
	v_add_u32_e32 v2, -1, v1
	v_fma_f32 v3, -v2, v1, v0
	v_cmp_ge_f32_e64 s[70:71], 0, v3
	v_add_u32_e32 v3, 1, v1
	s_nop 0
	v_cndmask_b32_e64 v2, v1, v2, s[70:71]
	v_fma_f32 v1, -v3, v1, v0
	v_cmp_lt_f32_e64 s[70:71], 0, v1
	s_nop 1
	v_cndmask_b32_e64 v1, v2, v3, s[70:71]
	v_mul_f32_e32 v2, 0x37800000, v1
	v_cndmask_b32_e32 v1, v1, v2, vcc
	v_cmp_class_f32_e32 vcc, v0, v207
	s_nop 1
	v_cndmask_b32_e32 v0, v1, v0, vcc
	v_div_scale_f32 v1, s[70:71], v0, v0, 1.0
	v_rcp_f32_e32 v2, v1
	s_nop 0
	v_fma_f32 v3, -v1, v2, 1.0
	v_fmac_f32_e32 v2, v3, v2
	v_div_scale_f32 v3, vcc, 1.0, v0, 1.0
	v_mul_f32_e32 v4, v3, v2
	v_fma_f32 v5, -v1, v4, v3
	v_fmac_f32_e32 v4, v5, v2
	v_fma_f32 v1, -v1, v4, v3
	v_div_fmas_f32 v1, v1, v2, v4
	v_div_fixup_f32 v0, v1, v0, 1.0
	v_mul_f32_e32 v215, 0x3db504f3, v0
	ds_read_b128 v[0:3], v190
	ds_read_b128 v[4:7], v190 offset:16
	v_mul_f32_e32 v21, v215, v21
	v_mul_f32_e32 v20, v215, v20
	v_mul_f32_e32 v22, v215, v22
	s_waitcnt lgkmcnt(1)
	v_mul_f32_e32 v1, v1, v21
	v_mul_f32_e32 v0, v0, v20
	v_mul_f32_e32 v216, v1, v1
	v_mul_f32_e32 v23, v215, v23
	v_mul_f32_e32 v2, v2, v22
	v_fmac_f32_e32 v216, v0, v0
	v_mul_f32_e32 v26, v215, v26
	v_mul_f32_e32 v3, v3, v23
	v_fmac_f32_e32 v216, v2, v2
	v_mul_f32_e32 v27, v215, v27
	s_waitcnt lgkmcnt(0)
	v_mul_f32_e32 v4, v4, v26
	v_fmac_f32_e32 v216, v3, v3
	v_mul_f32_e32 v30, v215, v30
	v_mul_f32_e32 v5, v5, v27
	v_fmac_f32_e32 v216, v4, v4
	v_mul_f32_e32 v31, v215, v31
	v_mul_f32_e32 v6, v6, v30
	v_fmac_f32_e32 v216, v5, v5
	v_mul_f32_e32 v7, v7, v31
	v_fmac_f32_e32 v216, v6, v6
	v_fmac_f32_e32 v216, v7, v7
	v_cvt_pk_bf16_f32 v32, v0, v1
	v_cvt_pk_bf16_f32 v33, v2, v3
	v_cvt_pk_bf16_f32 v34, v4, v5
	v_cvt_pk_bf16_f32 v35, v6, v7
	ds_read_b128 v[0:3], v190 offset:64
	ds_read_b128 v[4:7], v190 offset:80
	v_mul_f32_e32 v20, v215, v24
	v_mul_f32_e32 v21, v215, v25
	v_mul_f32_e32 v22, v215, v28
	s_waitcnt lgkmcnt(1)
	v_mul_f32_e32 v0, v0, v20
	v_mul_f32_e32 v1, v1, v21
	v_fmac_f32_e32 v216, v0, v0
	v_mul_f32_e32 v23, v215, v29
	v_mul_f32_e32 v2, v2, v22
	v_fmac_f32_e32 v216, v1, v1
	v_mul_f32_e32 v24, v215, v36
	v_mul_f32_e32 v3, v3, v23
	v_fmac_f32_e32 v216, v2, v2
	v_mul_f32_e32 v25, v215, v37
	s_waitcnt lgkmcnt(0)
	v_mul_f32_e32 v4, v24, v4
	v_fmac_f32_e32 v216, v3, v3
	v_mul_f32_e32 v26, v215, v38
	v_mul_f32_e32 v5, v25, v5
	v_fmac_f32_e32 v216, v4, v4
	v_mul_f32_e32 v27, v215, v39
	v_mul_f32_e32 v6, v26, v6
	v_fmac_f32_e32 v216, v5, v5
	v_mul_f32_e32 v7, v27, v7
	v_fmac_f32_e32 v216, v6, v6
	v_fmac_f32_e32 v216, v7, v7
	v_cvt_pk_bf16_f32 v36, v0, v1
	v_cvt_pk_bf16_f32 v37, v2, v3
	v_cvt_pk_bf16_f32 v38, v4, v5
	v_cvt_pk_bf16_f32 v39, v6, v7
	ds_read_b128 v[0:3], v190 offset:128
	ds_read_b128 v[4:7], v190 offset:144
	v_mul_f32_e32 v20, v215, v40
	v_mul_f32_e32 v21, v215, v41
	v_mul_f32_e32 v22, v215, v42
	s_waitcnt lgkmcnt(1)
	v_mul_f32_e32 v0, v20, v0
	v_mul_f32_e32 v1, v21, v1
	v_fmac_f32_e32 v216, v0, v0
	v_mul_f32_e32 v23, v215, v43
	v_mul_f32_e32 v2, v22, v2
	v_fmac_f32_e32 v216, v1, v1
	v_mul_f32_e32 v24, v215, v45
	v_mul_f32_e32 v3, v23, v3
	v_fmac_f32_e32 v216, v2, v2
	v_mul_f32_e32 v25, v215, v46
	s_waitcnt lgkmcnt(0)
	v_mul_f32_e32 v4, v24, v4
	v_fmac_f32_e32 v216, v3, v3
	v_mul_f32_e32 v26, v215, v48
	v_mul_f32_e32 v5, v25, v5
	v_fmac_f32_e32 v216, v4, v4
	v_mul_f32_e32 v27, v215, v49
	v_mul_f32_e32 v6, v26, v6
	v_fmac_f32_e32 v216, v5, v5
	v_mul_f32_e32 v7, v27, v7
	v_fmac_f32_e32 v216, v6, v6
	v_fmac_f32_e32 v216, v7, v7
	v_cvt_pk_bf16_f32 v40, v0, v1
	v_cvt_pk_bf16_f32 v41, v2, v3
	v_cvt_pk_bf16_f32 v42, v4, v5
	v_cvt_pk_bf16_f32 v43, v6, v7
	ds_read_b128 v[0:3], v190 offset:192
	ds_read_b128 v[4:7], v190 offset:208
	v_mul_f32_e32 v20, v215, v44
	v_mul_f32_e32 v16, v215, v16
	v_mul_f32_e32 v21, v215, v47
	s_waitcnt lgkmcnt(1)
	v_mul_f32_e32 v0, v20, v0
	v_mul_f32_e32 v1, v16, v1
	v_fmac_f32_e32 v216, v0, v0
	v_mul_f32_e32 v17, v215, v17
	v_mul_f32_e32 v2, v21, v2
	v_fmac_f32_e32 v216, v1, v1
	v_mul_f32_e32 v22, v215, v50
	v_mul_f32_e32 v3, v17, v3
	v_fmac_f32_e32 v216, v2, v2
	v_mul_f32_e32 v23, v215, v51
	s_waitcnt lgkmcnt(0)
	v_mul_f32_e32 v4, v22, v4
	v_fmac_f32_e32 v216, v3, v3
	v_mul_f32_e32 v24, v215, v52
	v_mul_f32_e32 v5, v23, v5
	v_fmac_f32_e32 v216, v4, v4
	v_mul_f32_e32 v25, v215, v53
	v_mul_f32_e32 v6, v24, v6
	v_fmac_f32_e32 v216, v5, v5
	v_mul_f32_e32 v7, v25, v7
	v_fmac_f32_e32 v216, v6, v6
	v_fmac_f32_e32 v216, v7, v7
	v_cvt_pk_bf16_f32 v44, v0, v1
	v_cvt_pk_bf16_f32 v45, v2, v3
	v_cvt_pk_bf16_f32 v46, v4, v5
	v_cvt_pk_bf16_f32 v47, v6, v7
	ds_read_b128 v[0:3], v190 offset:256
	ds_read_b128 v[4:7], v190 offset:272
	v_mul_f32_e32 v16, v215, v18
	v_mul_f32_e32 v12, v215, v12
	v_mul_f32_e32 v17, v215, v19
	s_waitcnt lgkmcnt(1)
	v_mul_f32_e32 v0, v16, v0
	v_mul_f32_e32 v1, v12, v1
	v_fmac_f32_e32 v216, v0, v0
	v_mul_f32_e32 v13, v215, v13
	v_mul_f32_e32 v2, v17, v2
	v_fmac_f32_e32 v216, v1, v1
	v_mul_f32_e32 v18, v215, v54
	v_mul_f32_e32 v3, v13, v3
	v_fmac_f32_e32 v216, v2, v2
	v_mul_f32_e32 v14, v215, v14
	s_waitcnt lgkmcnt(0)
	v_mul_f32_e32 v4, v18, v4
	v_fmac_f32_e32 v216, v3, v3
	v_mul_f32_e32 v19, v215, v55
	v_mul_f32_e32 v5, v14, v5
	v_fmac_f32_e32 v216, v4, v4
	v_mul_f32_e32 v15, v215, v15
	v_mul_f32_e32 v6, v19, v6
	v_fmac_f32_e32 v216, v5, v5
	v_mul_f32_e32 v7, v15, v7
	v_fmac_f32_e32 v216, v6, v6
	v_fmac_f32_e32 v216, v7, v7
	v_cvt_pk_bf16_f32 v16, v0, v1
	v_cvt_pk_bf16_f32 v17, v2, v3
	v_cvt_pk_bf16_f32 v18, v4, v5
	v_cvt_pk_bf16_f32 v19, v6, v7
	ds_read_b128 v[0:3], v190 offset:320
	ds_read_b128 v[4:7], v190 offset:336
	v_mul_f32_e32 v12, v215, v56
	v_mul_f32_e32 v8, v215, v8
	v_mul_f32_e32 v13, v215, v57
	s_waitcnt lgkmcnt(1)
	v_mul_f32_e32 v0, v12, v0
	v_mul_f32_e32 v1, v8, v1
	v_fmac_f32_e32 v216, v0, v0
	v_mul_f32_e32 v9, v215, v9
	v_mul_f32_e32 v2, v13, v2
	v_fmac_f32_e32 v216, v1, v1
	v_mul_f32_e32 v14, v215, v58
	v_mul_f32_e32 v3, v9, v3
	v_fmac_f32_e32 v216, v2, v2
	v_mul_f32_e32 v10, v215, v10
	s_waitcnt lgkmcnt(0)
	v_mul_f32_e32 v4, v14, v4
	v_fmac_f32_e32 v216, v3, v3
	v_mul_f32_e32 v15, v215, v59
	v_mul_f32_e32 v5, v10, v5
	v_fmac_f32_e32 v216, v4, v4
	v_mul_f32_e32 v11, v215, v11
	v_mul_f32_e32 v6, v15, v6
	v_fmac_f32_e32 v216, v5, v5
	v_mul_f32_e32 v7, v11, v7
	v_fmac_f32_e32 v216, v6, v6
	v_fmac_f32_e32 v216, v7, v7
	v_cvt_pk_bf16_f32 v20, v0, v1
	v_cvt_pk_bf16_f32 v21, v2, v3
	v_cvt_pk_bf16_f32 v22, v4, v5
	v_cvt_pk_bf16_f32 v23, v6, v7
	ds_read_b128 v[0:3], v190 offset:384
	ds_read_b128 v[4:7], v190 offset:400
	v_mul_f32_e32 v8, v215, v191
	v_mul_f32_e32 v9, v215, v192
	v_mul_f32_e32 v10, v215, v193
	s_waitcnt lgkmcnt(1)
	v_mul_f32_e32 v0, v8, v0
	v_mul_f32_e32 v1, v9, v1
	v_fmac_f32_e32 v216, v0, v0
	v_mul_f32_e32 v11, v215, v194
	v_mul_f32_e32 v2, v10, v2
	v_fmac_f32_e32 v216, v1, v1
	v_mul_f32_e32 v12, v215, v195
	v_mul_f32_e32 v3, v11, v3
	v_fmac_f32_e32 v216, v2, v2
	v_mul_f32_e32 v13, v215, v196
	s_waitcnt lgkmcnt(0)
	v_mul_f32_e32 v4, v12, v4
	v_fmac_f32_e32 v216, v3, v3
	v_mul_f32_e32 v14, v215, v197
	v_mul_f32_e32 v5, v13, v5
	v_fmac_f32_e32 v216, v4, v4
	v_mul_f32_e32 v15, v215, v198
	v_mul_f32_e32 v6, v14, v6
	v_fmac_f32_e32 v216, v5, v5
	v_mul_f32_e32 v7, v15, v7
	v_fmac_f32_e32 v216, v6, v6
	v_fmac_f32_e32 v216, v7, v7
	v_cvt_pk_bf16_f32 v24, v0, v1
	v_cvt_pk_bf16_f32 v25, v2, v3
	v_cvt_pk_bf16_f32 v26, v4, v5
	v_cvt_pk_bf16_f32 v27, v6, v7
	ds_read_b128 v[0:3], v190 offset:448
	ds_read_b128 v[4:7], v190 offset:464
	v_mul_f32_e32 v8, v215, v199
	v_mul_f32_e32 v9, v215, v200
	v_mul_f32_e32 v10, v215, v201
	s_waitcnt lgkmcnt(1)
	v_mul_f32_e32 v0, v8, v0
	v_mul_f32_e32 v1, v9, v1
	v_fmac_f32_e32 v216, v0, v0
	v_mul_f32_e32 v11, v215, v202
	v_mul_f32_e32 v2, v10, v2
	v_fmac_f32_e32 v216, v1, v1
	v_mul_f32_e32 v12, v215, v203
	v_mul_f32_e32 v3, v11, v3
	v_fmac_f32_e32 v216, v2, v2
	v_mul_f32_e32 v13, v215, v204
	s_waitcnt lgkmcnt(0)
	v_mul_f32_e32 v4, v12, v4
	v_fmac_f32_e32 v216, v3, v3
	v_mul_f32_e32 v14, v215, v205
	v_mul_f32_e32 v5, v13, v5
	v_fmac_f32_e32 v216, v4, v4
	v_mul_f32_e32 v15, v215, v214
	v_mul_f32_e32 v6, v14, v6
	v_fmac_f32_e32 v216, v5, v5
	v_mul_f32_e32 v7, v15, v7
	v_fmac_f32_e32 v216, v6, v6
	v_fmac_f32_e32 v216, v7, v7
	v_cvt_pk_bf16_f32 v28, v0, v1
	v_mov_b32_e32 v0, v216
	s_nop 1
	v_permlane32_swap_b32_e32 v216, v0
	v_add_f32_e32 v0, v216, v0
	v_cmp_gt_f32_e32 vcc, s72, v0
	v_mul_f32_e32 v1, 0x4f800000, v0
	v_cvt_pk_bf16_f32 v29, v2, v3
	v_cvt_pk_bf16_f32 v30, v4, v5
	v_cvt_pk_bf16_f32 v31, v6, v7
	s_nop 0
	v_cndmask_b32_e32 v0, v0, v1, vcc
	v_sqrt_f32_e32 v1, v0
	s_nop 0
	v_add_u32_e32 v2, -1, v1
	v_fma_f32 v3, -v2, v1, v0
	v_cmp_ge_f32_e64 s[70:71], 0, v3
	v_add_u32_e32 v3, 1, v1
	s_nop 0
	v_cndmask_b32_e64 v2, v1, v2, s[70:71]
	v_fma_f32 v1, -v3, v1, v0
	v_cmp_lt_f32_e64 s[70:71], 0, v1
	s_nop 1
	v_cndmask_b32_e64 v1, v2, v3, s[70:71]
	v_mul_f32_e32 v2, 0x37800000, v1
	v_cndmask_b32_e32 v1, v1, v2, vcc
	v_cmp_class_f32_e32 vcc, v0, v207
	v_readlane_b32 s70, v251, 47
	v_readlane_b32 s71, v251, 48
	v_cndmask_b32_e32 v0, v1, v0, vcc
	v_fma_f32 v199, v113, v0, v112
	global_load_dwordx4 v[0:3], v[60:61], off
	global_load_dwordx4 v[48:51], v[60:61], off offset:32
	global_load_dwordx4 v[52:55], v[60:61], off offset:64
	global_load_dwordx4 v[56:59], v[60:61], off offset:96
	s_waitcnt vmcnt(3)
	v_mfma_f32_32x32x16_bf16 v[0:15], v[0:3], v[32:35], 0
	s_waitcnt vmcnt(2)
	v_mfma_f32_32x32x16_bf16 v[0:15], v[48:51], v[36:39], v[0:15]
	s_waitcnt vmcnt(1)
	v_mfma_f32_32x32x16_bf16 v[0:15], v[52:55], v[40:43], v[0:15]
	s_waitcnt vmcnt(0)
	v_mfma_f32_32x32x16_bf16 v[0:15], v[56:59], v[44:47], v[0:15]
	global_load_dwordx4 v[48:51], v[60:61], off offset:128
	global_load_dwordx4 v[52:55], v[60:61], off offset:160
	global_load_dwordx4 v[56:59], v[60:61], off offset:192
	global_load_dwordx4 v[192:195], v[60:61], off offset:224
	s_waitcnt vmcnt(3)
	v_mfma_f32_32x32x16_bf16 v[0:15], v[48:51], v[16:19], v[0:15]
	v_add_u32_e32 v48, s33, v118
	ds_read_b32 v48, v48
	s_waitcnt lgkmcnt(0)
	v_fmac_f32_e32 v48, 0xbfb8aa3b, v199
	s_waitcnt vmcnt(2)
	v_mfma_f32_32x32x16_bf16 v[0:15], v[52:55], v[20:23], v[0:15]
	s_waitcnt vmcnt(1)
	v_mfma_f32_32x32x16_bf16 v[0:15], v[56:59], v[24:27], v[0:15]
	s_waitcnt vmcnt(0)
	v_mfma_f32_32x32x16_bf16 v[0:15], v[192:195], v[28:31], v[0:15]
	s_nop 11
	v_fmac_f32_e32 v48, 0x3fb8aa3b, v0
	v_exp_f32_e32 v0, v48
	v_add_u32_e32 v49, s33, v119
	ds_read_b32 v49, v49
	v_add_u32_e32 v50, s33, v120
	ds_read_b32 v50, v50
	v_add_u32_e32 v51, s33, v121
	ds_read_b32 v51, v51
	v_add_u32_e32 v52, s33, v122
	ds_read_b32 v52, v52
	v_add_u32_e32 v53, s33, v123
	ds_read_b32 v53, v53
	v_add_u32_e32 v54, s33, v189
	ds_read_b32 v54, v54
	v_add_u32_e32 v55, s33, v188
	ds_read_b32 v55, v55
	v_add_u32_e32 v56, s33, v187
	ds_read_b32 v56, v56
	v_add_u32_e32 v57, s33, v186
	ds_read_b32 v57, v57
	v_add_u32_e32 v58, s33, v185
	ds_read_b32 v58, v58
	v_add_u32_e32 v59, s33, v184
	ds_read_b32 v59, v59
	v_cndmask_b32_e64 v215, 0, v0, s[70:71]
	v_readlane_b32 s70, v251, 49
	v_readlane_b32 s71, v251, 50
	s_waitcnt lgkmcnt(10)
	v_fmac_f32_e32 v49, 0xbfb8aa3b, v199
	v_fmac_f32_e32 v49, 0x3fb8aa3b, v1
	v_exp_f32_e32 v1, v49
	v_add_f32_e32 v0, 0, v215
	v_cndmask_b32_e64 v214, 0, v1, s[70:71]
	v_readlane_b32 s70, v251, 51
	v_readlane_b32 s71, v251, 52
	v_add_f32_e32 v0, v0, v214
	s_waitcnt lgkmcnt(9)
	v_fmac_f32_e32 v50, 0xbfb8aa3b, v199
	v_fmac_f32_e32 v50, 0x3fb8aa3b, v2
	v_exp_f32_e32 v50, v50
	s_nop 0
	v_cndmask_b32_e64 v205, 0, v50, s[70:71]
	v_readlane_b32 s70, v251, 53
	v_readlane_b32 s71, v251, 54
	v_add_f32_e32 v0, v0, v205
	s_waitcnt lgkmcnt(8)
	v_fmac_f32_e32 v51, 0xbfb8aa3b, v199
	v_fmac_f32_e32 v51, 0x3fb8aa3b, v3
	v_exp_f32_e32 v51, v51
	s_nop 0
	v_cndmask_b32_e64 v204, 0, v51, s[70:71]
	v_readlane_b32 s70, v251, 55
	v_readlane_b32 s71, v251, 56
	v_add_f32_e32 v0, v0, v204
	s_waitcnt lgkmcnt(7)
	v_fmac_f32_e32 v52, 0xbfb8aa3b, v199
	v_fmac_f32_e32 v52, 0x3fb8aa3b, v4
	v_exp_f32_e32 v52, v52
	s_nop 0
	v_cndmask_b32_e64 v203, 0, v52, s[70:71]
	v_readlane_b32 s70, v251, 57
	v_readlane_b32 s71, v251, 58
	v_add_f32_e32 v0, v0, v203
	s_waitcnt lgkmcnt(6)
	v_fmac_f32_e32 v53, 0xbfb8aa3b, v199
	v_fmac_f32_e32 v53, 0x3fb8aa3b, v5
	v_exp_f32_e32 v53, v53
	s_nop 0
	v_cndmask_b32_e64 v202, 0, v53, s[70:71]
	v_readlane_b32 s70, v251, 59
	v_readlane_b32 s71, v251, 60
	v_add_f32_e32 v0, v0, v202
	s_waitcnt lgkmcnt(5)
	v_fmac_f32_e32 v54, 0xbfb8aa3b, v199
	v_fmac_f32_e32 v54, 0x3fb8aa3b, v6
	v_exp_f32_e32 v54, v54
	s_nop 0
	v_cndmask_b32_e64 v201, 0, v54, s[70:71]
	v_readlane_b32 s70, v251, 61
	v_readlane_b32 s71, v251, 62
	v_add_f32_e32 v0, v0, v201
	s_waitcnt lgkmcnt(4)
	v_fmac_f32_e32 v55, 0xbfb8aa3b, v199
	v_fmac_f32_e32 v55, 0x3fb8aa3b, v7
	v_exp_f32_e32 v55, v55
	s_nop 0
	v_cndmask_b32_e64 v200, 0, v55, s[70:71]
	v_readlane_b32 s70, v251, 63
	v_readlane_b32 s71, v255, 0
	v_add_f32_e32 v0, v0, v200
	s_waitcnt lgkmcnt(3)
	v_fmac_f32_e32 v56, 0xbfb8aa3b, v199
	v_fmac_f32_e32 v56, 0x3fb8aa3b, v8
	v_exp_f32_e32 v56, v56
	s_nop 0
	v_cndmask_b32_e64 v198, 0, v56, s[70:71]
	v_readlane_b32 s70, v255, 1
	v_readlane_b32 s71, v255, 2
	v_add_f32_e32 v0, v0, v198
	s_waitcnt lgkmcnt(2)
	v_fmac_f32_e32 v57, 0xbfb8aa3b, v199
	v_fmac_f32_e32 v57, 0x3fb8aa3b, v9
	v_exp_f32_e32 v57, v57
	s_nop 0
	v_cndmask_b32_e64 v197, 0, v57, s[70:71]
	v_readlane_b32 s70, v255, 3
	v_readlane_b32 s71, v255, 4
	v_add_f32_e32 v0, v0, v197
	s_waitcnt lgkmcnt(1)
	v_fmac_f32_e32 v58, 0xbfb8aa3b, v199
	v_fmac_f32_e32 v58, 0x3fb8aa3b, v10
	v_exp_f32_e32 v58, v58
	s_nop 0
	v_cndmask_b32_e64 v196, 0, v58, s[70:71]
	v_readlane_b32 s70, v255, 5
	v_readlane_b32 s71, v255, 6
	v_add_f32_e32 v0, v0, v196
	s_waitcnt lgkmcnt(0)
	v_fmac_f32_e32 v59, 0xbfb8aa3b, v199
	v_fmac_f32_e32 v59, 0x3fb8aa3b, v11
	v_exp_f32_e32 v59, v59
	s_nop 0
	v_cndmask_b32_e64 v195, 0, v59, s[70:71]
	v_add_u32_e32 v49, s33, v183
	ds_read_b32 v49, v49
	v_add_u32_e32 v50, s33, v182
	ds_read_b32 v50, v50
	v_add_u32_e32 v51, s33, v181
	ds_read_b32 v51, v51
	v_add_u32_e32 v52, s33, v180
	ds_read_b32 v52, v52
	v_readlane_b32 s70, v255, 7
	v_readlane_b32 s71, v255, 8
	v_add_f32_e32 v0, v0, v195
	s_waitcnt lgkmcnt(3)
	v_fmac_f32_e32 v49, 0xbfb8aa3b, v199
	v_fmac_f32_e32 v49, 0x3fb8aa3b, v12
	v_exp_f32_e32 v49, v49
	s_nop 0
	v_cndmask_b32_e64 v194, 0, v49, s[70:71]
	v_readlane_b32 s70, v255, 9
	v_readlane_b32 s71, v255, 10
	v_add_f32_e32 v0, v0, v194
	s_waitcnt lgkmcnt(2)
	v_fmac_f32_e32 v50, 0xbfb8aa3b, v199
	v_fmac_f32_e32 v50, 0x3fb8aa3b, v13
	v_exp_f32_e32 v50, v50
	s_nop 0
	v_cndmask_b32_e64 v193, 0, v50, s[70:71]
	v_readlane_b32 s70, v255, 11
	v_readlane_b32 s71, v255, 12
	v_add_f32_e32 v0, v0, v193
	s_waitcnt lgkmcnt(1)
	v_fmac_f32_e32 v51, 0xbfb8aa3b, v199
	v_fmac_f32_e32 v51, 0x3fb8aa3b, v14
	v_exp_f32_e32 v51, v51
	s_nop 0
	v_cndmask_b32_e64 v192, 0, v51, s[70:71]
	v_readlane_b32 s70, v255, 13
	v_readlane_b32 s71, v255, 14
	v_add_f32_e32 v0, v0, v192
	s_waitcnt lgkmcnt(0)
	v_fmac_f32_e32 v52, 0xbfb8aa3b, v199
	v_fmac_f32_e32 v52, 0x3fb8aa3b, v15
	v_exp_f32_e32 v52, v52
	s_nop 0
	v_cndmask_b32_e64 v191, 0, v52, s[70:71]
	v_add_f32_e32 v216, v0, v191
	global_load_dwordx4 v[0:3], v[62:63], off
	global_load_dwordx4 v[48:51], v[64:65], off
	global_load_dwordx4 v[52:55], v[66:67], off
	global_load_dwordx4 v[56:59], v[68:69], off
	s_waitcnt vmcnt(3)
	v_mfma_f32_32x32x16_bf16 v[0:15], v[0:3], v[32:35], 0
	v_readlane_b32 s70, v255, 15
	v_readlane_b32 s71, v255, 16
	s_waitcnt vmcnt(2)
	v_mfma_f32_32x32x16_bf16 v[0:15], v[48:51], v[36:39], v[0:15]
	s_waitcnt vmcnt(1)
	v_mfma_f32_32x32x16_bf16 v[0:15], v[52:55], v[40:43], v[0:15]
	s_waitcnt vmcnt(0)
	v_mfma_f32_32x32x16_bf16 v[0:15], v[56:59], v[44:47], v[0:15]
	global_load_dwordx4 v[48:51], v[70:71], off
	global_load_dwordx4 v[52:55], v[72:73], off
	global_load_dwordx4 v[56:59], v[74:75], off
	global_load_dwordx4 v[218:221], v[76:77], off
	s_waitcnt vmcnt(3)
	v_mfma_f32_32x32x16_bf16 v[0:15], v[48:51], v[16:19], v[0:15]
	v_add_u32_e32 v48, s33, v179
	ds_read_b32 v48, v48
	s_waitcnt lgkmcnt(0)
	v_fmac_f32_e32 v48, 0xbfb8aa3b, v199
	s_waitcnt vmcnt(2)
	v_mfma_f32_32x32x16_bf16 v[0:15], v[52:55], v[20:23], v[0:15]
	s_waitcnt vmcnt(1)
	v_mfma_f32_32x32x16_bf16 v[0:15], v[56:59], v[24:27], v[0:15]
	s_waitcnt vmcnt(0)
	v_mfma_f32_32x32x16_bf16 v[0:15], v[218:221], v[28:31], v[0:15]
	v_add_u32_e32 v221, s33, v163
	s_nop 10
	v_fmac_f32_e32 v48, 0x3fb8aa3b, v0
	v_exp_f32_e32 v0, v48
	v_add_u32_e32 v222, s33, v178
	ds_read_b32 v222, v222
	v_add_u32_e32 v223, s33, v177
	ds_read_b32 v223, v223
	v_add_u32_e32 v224, s33, v176
	ds_read_b32 v224, v224
	v_add_u32_e32 v225, s33, v175
	ds_read_b32 v225, v225
	v_add_u32_e32 v226, s33, v174
	ds_read_b32 v226, v226
	v_add_u32_e32 v227, s33, v173
	ds_read_b32 v227, v227
	v_add_u32_e32 v228, s33, v172
	ds_read_b32 v228, v228
	v_add_u32_e32 v229, s33, v171
	ds_read_b32 v229, v229
	v_add_u32_e32 v230, s33, v170
	ds_read_b32 v230, v230
	v_add_u32_e32 v231, s33, v169
	ds_read_b32 v231, v231
	v_add_u32_e32 v232, s33, v168
	ds_read_b32 v232, v232
	v_add_u32_e32 v233, s33, v167
	ds_read_b32 v233, v233
	v_cndmask_b32_e64 v219, 0, v0, s[70:71]
	v_readlane_b32 s70, v255, 17
	v_readlane_b32 s71, v255, 18
	s_waitcnt lgkmcnt(11)
	v_fmac_f32_e32 v222, 0xbfb8aa3b, v199
	v_fmac_f32_e32 v222, 0x3fb8aa3b, v1
	v_exp_f32_e32 v1, v222
	v_add_f32_e32 v0, v216, v219
	v_cndmask_b32_e64 v218, 0, v1, s[70:71]
	v_add_f32_e32 v0, v0, v218
	s_waitcnt lgkmcnt(10)
	v_fmac_f32_e32 v223, 0xbfb8aa3b, v199
	v_fmac_f32_e32 v223, 0x3fb8aa3b, v2
	v_exp_f32_e32 v223, v223
	s_nop 0
	v_cndmask_b32_e64 v217, 0, v223, s[74:75]
	v_add_f32_e32 v0, v0, v217
	s_waitcnt lgkmcnt(9)
	v_fmac_f32_e32 v224, 0xbfb8aa3b, v199
	v_fmac_f32_e32 v224, 0x3fb8aa3b, v3
	v_exp_f32_e32 v224, v224
	s_nop 0
	v_cndmask_b32_e64 v216, 0, v224, s[76:77]
	v_add_f32_e32 v0, v0, v216
	s_waitcnt lgkmcnt(8)
	v_fmac_f32_e32 v225, 0xbfb8aa3b, v199
	v_fmac_f32_e32 v225, 0x3fb8aa3b, v4
	v_exp_f32_e32 v225, v225
	s_nop 0
	v_cndmask_b32_e64 v59, 0, v225, s[78:79]
	v_add_f32_e32 v0, v0, v59
	s_waitcnt lgkmcnt(7)
	v_fmac_f32_e32 v226, 0xbfb8aa3b, v199
	v_fmac_f32_e32 v226, 0x3fb8aa3b, v5
	v_exp_f32_e32 v226, v226
	s_nop 0
	v_cndmask_b32_e64 v58, 0, v226, s[80:81]
	v_add_f32_e32 v0, v0, v58
	s_waitcnt lgkmcnt(6)
	v_fmac_f32_e32 v227, 0xbfb8aa3b, v199
	v_fmac_f32_e32 v227, 0x3fb8aa3b, v6
	v_exp_f32_e32 v227, v227
	s_nop 0
	v_cndmask_b32_e64 v57, 0, v227, s[82:83]
	v_add_f32_e32 v0, v0, v57
	s_waitcnt lgkmcnt(5)
	v_fmac_f32_e32 v228, 0xbfb8aa3b, v199
	v_fmac_f32_e32 v228, 0x3fb8aa3b, v7
	v_exp_f32_e32 v228, v228
	s_nop 0
	v_cndmask_b32_e64 v56, 0, v228, s[84:85]
	v_add_f32_e32 v0, v0, v56
	s_waitcnt lgkmcnt(4)
	v_fmac_f32_e32 v229, 0xbfb8aa3b, v199
	v_fmac_f32_e32 v229, 0x3fb8aa3b, v8
	v_exp_f32_e32 v229, v229
	s_nop 0
	v_cndmask_b32_e64 v55, 0, v229, s[86:87]
	v_add_f32_e32 v0, v0, v55
	s_waitcnt lgkmcnt(3)
	v_fmac_f32_e32 v230, 0xbfb8aa3b, v199
	v_fmac_f32_e32 v230, 0x3fb8aa3b, v9
	v_exp_f32_e32 v230, v230
	s_nop 0
	v_cndmask_b32_e64 v54, 0, v230, s[88:89]
	v_add_f32_e32 v0, v0, v54
	s_waitcnt lgkmcnt(2)
	v_fmac_f32_e32 v231, 0xbfb8aa3b, v199
	v_fmac_f32_e32 v231, 0x3fb8aa3b, v10
	v_exp_f32_e32 v231, v231
	s_nop 0
	v_cndmask_b32_e64 v53, 0, v231, s[90:91]
	v_add_f32_e32 v0, v0, v53
	s_waitcnt lgkmcnt(1)
	v_fmac_f32_e32 v232, 0xbfb8aa3b, v199
	v_fmac_f32_e32 v232, 0x3fb8aa3b, v11
	v_exp_f32_e32 v232, v232
	s_nop 0
	v_cndmask_b32_e64 v52, 0, v232, s[92:93]
	v_add_f32_e32 v0, v0, v52
	s_waitcnt lgkmcnt(0)
	v_fmac_f32_e32 v233, 0xbfb8aa3b, v199
	v_fmac_f32_e32 v233, 0x3fb8aa3b, v12
	v_exp_f32_e32 v233, v233
	s_nop 0
	v_cndmask_b32_e64 v51, 0, v233, s[94:95]
	v_add_u32_e32 v222, s33, v166
	ds_read_b32 v222, v222
	v_add_u32_e32 v223, s33, v165
	ds_read_b32 v223, v223
	v_add_u32_e32 v224, s33, v164
	ds_read_b32 v224, v224
	v_add_f32_e32 v0, v0, v51
	s_waitcnt lgkmcnt(2)
	v_fmac_f32_e32 v222, 0xbfb8aa3b, v199
	v_fmac_f32_e32 v222, 0x3fb8aa3b, v13
	v_exp_f32_e32 v222, v222
	s_nop 0
	v_cndmask_b32_e64 v50, 0, v222, s[96:97]
	v_add_f32_e32 v0, v0, v50
	s_waitcnt lgkmcnt(1)
	v_fmac_f32_e32 v223, 0xbfb8aa3b, v199
	v_fmac_f32_e32 v223, 0x3fb8aa3b, v14
	v_exp_f32_e32 v223, v223
	s_nop 0
	v_cndmask_b32_e64 v49, 0, v223, s[4:5]
	v_add_f32_e32 v0, v0, v49
	s_waitcnt lgkmcnt(0)
	v_fmac_f32_e32 v224, 0xbfb8aa3b, v199
	v_fmac_f32_e32 v224, 0x3fb8aa3b, v15
	v_exp_f32_e32 v224, v224
	s_nop 0
	v_cndmask_b32_e64 v48, 0, v224, s[6:7]
	v_add_f32_e32 v220, v0, v48
	global_load_dwordx4 v[0:3], v[78:79], off
	global_load_dwordx4 v[222:225], v[80:81], off
	global_load_dwordx4 v[226:229], v[82:83], off
	global_load_dwordx4 v[230:233], v[84:85], off
	s_waitcnt vmcnt(3)
	v_mfma_f32_32x32x16_bf16 v[0:15], v[0:3], v[32:35], 0
	s_waitcnt vmcnt(2)
	v_mfma_f32_32x32x16_bf16 v[0:15], v[222:225], v[36:39], v[0:15]
	s_waitcnt vmcnt(1)
	v_mfma_f32_32x32x16_bf16 v[0:15], v[226:229], v[40:43], v[0:15]
	s_waitcnt vmcnt(0)
	v_mfma_f32_32x32x16_bf16 v[0:15], v[230:233], v[44:47], v[0:15]
	global_load_dwordx4 v[222:225], v[86:87], off
	global_load_dwordx4 v[226:229], v[88:89], off
	global_load_dwordx4 v[230:233], v[90:91], off
	global_load_dwordx4 v[234:237], v[92:93], off
	ds_read_b32 v221, v221
	s_waitcnt lgkmcnt(0)
	v_fmac_f32_e32 v221, 0xbfb8aa3b, v199
	s_waitcnt vmcnt(3)
	v_mfma_f32_32x32x16_bf16 v[0:15], v[222:225], v[16:19], v[0:15]
	s_waitcnt vmcnt(2)
	v_mfma_f32_32x32x16_bf16 v[0:15], v[226:229], v[20:23], v[0:15]
	s_waitcnt vmcnt(1)
	v_mfma_f32_32x32x16_bf16 v[0:15], v[230:233], v[24:27], v[0:15]
	s_waitcnt vmcnt(0)
	v_mfma_f32_32x32x16_bf16 v[0:15], v[234:237], v[28:31], v[0:15]
	s_nop 11
	v_fmac_f32_e32 v221, 0x3fb8aa3b, v0
	v_exp_f32_e32 v0, v221
	s_nop 0
	v_cndmask_b32_e64 v235, 0, v0, s[8:9]
	v_add_f32_e32 v0, v220, v235
	v_add_u32_e32 v238, s33, v162
	ds_read_b32 v238, v238
	v_add_u32_e32 v239, s33, v155
	ds_read_b32 v239, v239
	v_add_u32_e32 v240, s33, v152
	ds_read_b32 v240, v240
	v_add_u32_e32 v241, s33, v151
	ds_read_b32 v241, v241
	v_add_u32_e32 v242, s33, v150
	ds_read_b32 v242, v242
	v_add_u32_e32 v243, s33, v149
	ds_read_b32 v243, v243
	v_add_u32_e32 v244, s33, v148
	ds_read_b32 v244, v244
	v_add_u32_e32 v245, s33, v147
	ds_read_b32 v245, v245
	v_add_u32_e32 v246, s33, v146
	ds_read_b32 v246, v246
	v_add_u32_e32 v247, s33, v145
	ds_read_b32 v247, v247
	v_add_u32_e32 v248, s33, v144
	ds_read_b32 v248, v248
	v_add_u32_e32 v249, s33, v143
	ds_read_b32 v249, v249
	s_waitcnt lgkmcnt(11)
	v_fmac_f32_e32 v238, 0xbfb8aa3b, v199
	v_fmac_f32_e32 v238, 0x3fb8aa3b, v1
	v_exp_f32_e32 v1, v238
	s_nop 0
	v_cndmask_b32_e64 v234, 0, v1, s[10:11]
	v_add_f32_e32 v0, v0, v234
	s_waitcnt lgkmcnt(10)
	v_fmac_f32_e32 v239, 0xbfb8aa3b, v199
	v_fmac_f32_e32 v239, 0x3fb8aa3b, v2
	v_exp_f32_e32 v239, v239
	s_nop 0
	v_cndmask_b32_e64 v233, 0, v239, s[12:13]
	v_add_f32_e32 v0, v0, v233
	s_waitcnt lgkmcnt(9)
	v_fmac_f32_e32 v240, 0xbfb8aa3b, v199
	v_fmac_f32_e32 v240, 0x3fb8aa3b, v3
	v_exp_f32_e32 v240, v240
	s_nop 0
	v_cndmask_b32_e64 v232, 0, v240, s[14:15]
	v_add_f32_e32 v0, v0, v232
	s_waitcnt lgkmcnt(8)
	v_fmac_f32_e32 v241, 0xbfb8aa3b, v199
	v_fmac_f32_e32 v241, 0x3fb8aa3b, v4
	v_exp_f32_e32 v241, v241
	s_nop 0
	v_cndmask_b32_e64 v231, 0, v241, s[16:17]
	v_add_f32_e32 v0, v0, v231
	s_waitcnt lgkmcnt(7)
	v_fmac_f32_e32 v242, 0xbfb8aa3b, v199
	v_fmac_f32_e32 v242, 0x3fb8aa3b, v5
	v_exp_f32_e32 v242, v242
	s_nop 0
	v_cndmask_b32_e64 v230, 0, v242, s[18:19]
	v_add_f32_e32 v0, v0, v230
	s_waitcnt lgkmcnt(6)
	v_fmac_f32_e32 v243, 0xbfb8aa3b, v199
	v_fmac_f32_e32 v243, 0x3fb8aa3b, v6
	v_exp_f32_e32 v243, v243
	s_nop 0
	v_cndmask_b32_e64 v229, 0, v243, s[20:21]
	v_add_f32_e32 v0, v0, v229
	s_waitcnt lgkmcnt(5)
	v_fmac_f32_e32 v244, 0xbfb8aa3b, v199
	v_fmac_f32_e32 v244, 0x3fb8aa3b, v7
	v_exp_f32_e32 v244, v244
	s_nop 0
	v_cndmask_b32_e64 v228, 0, v244, s[22:23]
	v_add_f32_e32 v0, v0, v228
	s_waitcnt lgkmcnt(4)
	v_fmac_f32_e32 v245, 0xbfb8aa3b, v199
	v_fmac_f32_e32 v245, 0x3fb8aa3b, v8
	v_exp_f32_e32 v245, v245
	s_nop 0
	v_cndmask_b32_e64 v227, 0, v245, s[24:25]
	v_add_f32_e32 v0, v0, v227
	s_waitcnt lgkmcnt(3)
	v_fmac_f32_e32 v246, 0xbfb8aa3b, v199
	v_fmac_f32_e32 v246, 0x3fb8aa3b, v9
	v_exp_f32_e32 v246, v246
	s_nop 0
	v_cndmask_b32_e64 v226, 0, v246, s[26:27]
	v_add_f32_e32 v0, v0, v226
	s_waitcnt lgkmcnt(2)
	v_fmac_f32_e32 v247, 0xbfb8aa3b, v199
	v_fmac_f32_e32 v247, 0x3fb8aa3b, v10
	v_exp_f32_e32 v247, v247
	s_nop 0
	v_cndmask_b32_e64 v225, 0, v247, s[28:29]
	v_add_f32_e32 v0, v0, v225
	s_waitcnt lgkmcnt(1)
	v_fmac_f32_e32 v248, 0xbfb8aa3b, v199
	v_fmac_f32_e32 v248, 0x3fb8aa3b, v11
	v_exp_f32_e32 v248, v248
	s_nop 0
	v_cndmask_b32_e64 v224, 0, v248, s[30:31]
	v_add_f32_e32 v0, v0, v224
	s_waitcnt lgkmcnt(0)
	v_fmac_f32_e32 v249, 0xbfb8aa3b, v199
	v_fmac_f32_e32 v249, 0x3fb8aa3b, v12
	v_exp_f32_e32 v249, v249
	s_nop 0
	v_cndmask_b32_e64 v223, 0, v249, s[34:35]
	v_add_u32_e32 v238, s33, v142
	ds_read_b32 v238, v238
	v_add_u32_e32 v239, s33, v141
	ds_read_b32 v239, v239
	v_add_u32_e32 v240, s33, v140
	ds_read_b32 v240, v240
	v_add_f32_e32 v0, v0, v223
	s_waitcnt lgkmcnt(2)
	v_fmac_f32_e32 v238, 0xbfb8aa3b, v199
	v_fmac_f32_e32 v238, 0x3fb8aa3b, v13
	v_exp_f32_e32 v238, v238
	s_nop 0
	v_cndmask_b32_e64 v222, 0, v238, s[36:37]
	v_add_f32_e32 v0, v0, v222
	s_waitcnt lgkmcnt(1)
	v_fmac_f32_e32 v239, 0xbfb8aa3b, v199
	v_fmac_f32_e32 v239, 0x3fb8aa3b, v14
	v_exp_f32_e32 v239, v239
	s_nop 0
	v_cndmask_b32_e64 v221, 0, v239, s[38:39]
	v_add_f32_e32 v0, v0, v221
	s_waitcnt lgkmcnt(0)
	v_fmac_f32_e32 v240, 0xbfb8aa3b, v199
	v_fmac_f32_e32 v240, 0x3fb8aa3b, v15
	v_exp_f32_e32 v240, v240
	s_nop 0
	v_cndmask_b32_e64 v220, 0, v240, s[2:3]
	v_add_f32_e32 v236, v0, v220
	global_load_dwordx4 v[0:3], v[94:95], off
	global_load_dwordx4 v[238:241], v[96:97], off
	global_load_dwordx4 v[242:245], v[98:99], off
	global_load_dwordx4 v[246:249], v[100:101], off
	s_waitcnt vmcnt(3)
	v_mfma_f32_32x32x16_bf16 v[0:15], v[0:3], v[32:35], 0
	s_waitcnt vmcnt(2)
	v_mfma_f32_32x32x16_bf16 v[0:15], v[238:241], v[36:39], v[0:15]
	s_waitcnt vmcnt(1)
	v_mfma_f32_32x32x16_bf16 v[0:15], v[242:245], v[40:43], v[0:15]
	s_waitcnt vmcnt(0)
	v_mfma_f32_32x32x16_bf16 v[0:15], v[246:249], v[44:47], v[0:15]
	global_load_dwordx4 v[32:35], v[102:103], off
	global_load_dwordx4 v[40:43], v[104:105], off
	global_load_dwordx4 v[36:39], v[106:107], off
	global_load_dwordx4 v[44:47], v[108:109], off
	s_waitcnt vmcnt(3)
	v_mfma_f32_32x32x16_bf16 v[0:15], v[32:35], v[16:19], v[0:15]
	v_add_u32_e32 v16, s33, v139
	v_add_u32_e32 v17, s33, v138
	ds_read_b32 v16, v16
	ds_read_b32 v17, v17
	s_waitcnt lgkmcnt(1)
	v_fmac_f32_e32 v16, 0xbfb8aa3b, v199
	s_waitcnt vmcnt(2)
	v_mfma_f32_32x32x16_bf16 v[0:15], v[40:43], v[20:23], v[0:15]
	s_waitcnt lgkmcnt(0)
	v_fmac_f32_e32 v17, 0xbfb8aa3b, v199
	s_waitcnt vmcnt(1)
	v_mfma_f32_32x32x16_bf16 v[0:15], v[36:39], v[24:27], v[0:15]
	s_waitcnt vmcnt(0)
	v_mfma_f32_32x32x16_bf16 v[0:15], v[44:47], v[28:31], v[0:15]
	s_nop 11
	v_fmac_f32_e32 v17, 0x3fb8aa3b, v1
	v_exp_f32_e32 v1, v17
	v_add_u32_e32 v238, s33, v137
	ds_read_b32 v238, v238
	v_add_u32_e32 v239, s33, v136
	ds_read_b32 v239, v239
	v_add_u32_e32 v240, s33, v135
	ds_read_b32 v240, v240
	v_add_u32_e32 v241, s33, v134
	ds_read_b32 v241, v241
	v_add_u32_e32 v242, s33, v133
	ds_read_b32 v242, v242
	v_add_u32_e32 v243, s33, v132
	ds_read_b32 v243, v243
	v_add_u32_e32 v244, s33, v131
	ds_read_b32 v244, v244
	v_add_u32_e32 v245, s33, v130
	ds_read_b32 v245, v245
	v_add_u32_e32 v246, s33, v129
	ds_read_b32 v246, v246
	v_add_u32_e32 v247, s33, v128
	ds_read_b32 v247, v247
	v_add_u32_e32 v248, s33, v127
	ds_read_b32 v248, v248
	v_add_u32_e32 v249, s33, v126
	ds_read_b32 v249, v249
	v_fmac_f32_e32 v16, 0x3fb8aa3b, v0
	v_exp_f32_e32 v0, v16
	v_cndmask_b32_e64 v1, 0, v1, s[40:41]
	s_waitcnt lgkmcnt(11)
	v_fmac_f32_e32 v238, 0xbfb8aa3b, v199
	v_fmac_f32_e32 v238, 0x3fb8aa3b, v2
	v_exp_f32_e32 v2, v238
	v_cndmask_b32_e64 v0, 0, v0, s[0:1]
	v_add_f32_e32 v16, v236, v0
	v_add_f32_e32 v16, v16, v1
	v_cndmask_b32_e64 v2, 0, v2, s[42:43]
	s_waitcnt lgkmcnt(10)
	v_fmac_f32_e32 v239, 0xbfb8aa3b, v199
	v_fmac_f32_e32 v239, 0x3fb8aa3b, v3
	v_exp_f32_e32 v3, v239
	v_add_f32_e32 v16, v16, v2
	v_cndmask_b32_e64 v3, 0, v3, s[44:45]
	v_add_f32_e32 v16, v16, v3
	s_waitcnt lgkmcnt(9)
	v_fmac_f32_e32 v240, 0xbfb8aa3b, v199
	v_fmac_f32_e32 v240, 0x3fb8aa3b, v4
	v_exp_f32_e32 v4, v240
	s_nop 0
	v_cndmask_b32_e64 v4, 0, v4, s[46:47]
	v_add_f32_e32 v16, v16, v4
	s_waitcnt lgkmcnt(8)
	v_fmac_f32_e32 v241, 0xbfb8aa3b, v199
	v_fmac_f32_e32 v241, 0x3fb8aa3b, v5
	v_exp_f32_e32 v5, v241
	s_nop 0
	v_cndmask_b32_e64 v5, 0, v5, s[48:49]
	v_add_f32_e32 v16, v16, v5
	s_waitcnt lgkmcnt(7)
	v_fmac_f32_e32 v242, 0xbfb8aa3b, v199
	v_fmac_f32_e32 v242, 0x3fb8aa3b, v6
	v_exp_f32_e32 v6, v242
	s_nop 0
	v_cndmask_b32_e64 v6, 0, v6, s[50:51]
	v_add_f32_e32 v16, v16, v6
	s_waitcnt lgkmcnt(6)
	v_fmac_f32_e32 v243, 0xbfb8aa3b, v199
	v_fmac_f32_e32 v243, 0x3fb8aa3b, v7
	v_exp_f32_e32 v7, v243
	s_nop 0
	v_cndmask_b32_e64 v7, 0, v7, s[52:53]
	v_add_f32_e32 v16, v16, v7
	s_waitcnt lgkmcnt(5)
	v_fmac_f32_e32 v244, 0xbfb8aa3b, v199
	v_fmac_f32_e32 v244, 0x3fb8aa3b, v8
	v_exp_f32_e32 v8, v244
	s_nop 0
	v_cndmask_b32_e64 v8, 0, v8, s[54:55]
	v_add_f32_e32 v16, v16, v8
	s_waitcnt lgkmcnt(4)
	v_fmac_f32_e32 v245, 0xbfb8aa3b, v199
	v_fmac_f32_e32 v245, 0x3fb8aa3b, v9
	v_exp_f32_e32 v9, v245
	s_nop 0
	v_cndmask_b32_e64 v9, 0, v9, s[56:57]
	v_add_f32_e32 v16, v16, v9
	s_waitcnt lgkmcnt(3)
	v_fmac_f32_e32 v246, 0xbfb8aa3b, v199
	v_fmac_f32_e32 v246, 0x3fb8aa3b, v10
	v_exp_f32_e32 v10, v246
	s_nop 0
	v_cndmask_b32_e64 v10, 0, v10, s[58:59]
	v_add_f32_e32 v16, v16, v10
	s_waitcnt lgkmcnt(2)
	v_fmac_f32_e32 v247, 0xbfb8aa3b, v199
	v_fmac_f32_e32 v247, 0x3fb8aa3b, v11
	v_exp_f32_e32 v11, v247
	s_nop 0
	v_cndmask_b32_e64 v11, 0, v11, s[60:61]
	v_add_f32_e32 v16, v16, v11
	s_waitcnt lgkmcnt(1)
	v_fmac_f32_e32 v248, 0xbfb8aa3b, v199
	v_fmac_f32_e32 v248, 0x3fb8aa3b, v12
	v_exp_f32_e32 v12, v248
	s_nop 0
	v_cndmask_b32_e64 v12, 0, v12, s[62:63]
	v_add_f32_e32 v16, v16, v12
	s_waitcnt lgkmcnt(0)
	v_fmac_f32_e32 v249, 0xbfb8aa3b, v199
	v_fmac_f32_e32 v249, 0x3fb8aa3b, v13
	v_exp_f32_e32 v13, v249
	v_add_u32_e32 v238, s33, v125
	ds_read_b32 v238, v238
	v_add_u32_e32 v239, s33, v124
	ds_read_b32 v239, v239
	v_cndmask_b32_e64 v13, 0, v13, s[64:65]
	v_add_f32_e32 v16, v16, v13
	s_waitcnt lgkmcnt(1)
	v_fmac_f32_e32 v238, 0xbfb8aa3b, v199
	v_fmac_f32_e32 v238, 0x3fb8aa3b, v14
	v_exp_f32_e32 v14, v238
	s_nop 0
	v_cndmask_b32_e64 v14, 0, v14, s[66:67]
	v_add_f32_e32 v16, v16, v14
	s_waitcnt lgkmcnt(0)
	v_fmac_f32_e32 v239, 0xbfb8aa3b, v199
	v_fmac_f32_e32 v239, 0x3fb8aa3b, v15
	v_exp_f32_e32 v15, v239
	s_nop 0
	v_cndmask_b32_e64 v15, 0, v15, s[68:69]
	v_add_f32_e32 v16, v16, v15
	v_mov_b32_e32 v17, v16
	s_nop 1
	v_permlane32_swap_b32_e32 v16, v17
	v_add_f32_e32 v16, v16, v17
	v_div_scale_f32 v17, vcc, v16, v16, 1.0
	v_rcp_f32_e32 v18, v17
	v_cmp_lt_f32_e64 s[70:71], 0, v16
	v_fma_f32 v19, -v17, v18, 1.0
	v_fmac_f32_e32 v18, v19, v18
	v_div_scale_f32 v19, vcc, 1.0, v16, 1.0
	v_mul_f32_e32 v20, v19, v18
	v_fma_f32 v21, -v17, v20, v19
	v_fmac_f32_e32 v20, v21, v18
	v_fma_f32 v17, -v17, v20, v19
	v_div_fmas_f32 v17, v17, v18, v20
	v_div_fixup_f32 v16, v17, v16, 1.0
	v_cndmask_b32_e64 v16, 0, v16, s[70:71]
	s_cmp_eq_u32 s33, 0
	s_cbranch_scc1 .Lmy_ps_first
	ds_read_b32 v22, v117
	ds_read_b32 v23, v117 offset:128
	ds_read_b32 v24, v117 offset:256
	ds_read_b32 v25, v117 offset:384
	ds_read_b32 v26, v117 offset:1024
	ds_read_b32 v27, v117 offset:1152
	ds_read_b32 v28, v117 offset:1280
	ds_read_b32 v29, v117 offset:1408
	ds_read_b32 v30, v117 offset:2048
	ds_read_b32 v31, v117 offset:2176
	ds_read_b32 v32, v117 offset:2304
	ds_read_b32 v33, v117 offset:2432
	ds_read_b32 v34, v117 offset:3072
	ds_read_b32 v35, v117 offset:3200
	ds_read_b32 v36, v117 offset:3328
	ds_read_b32 v37, v117 offset:3456
	v_mul_f32_e32 v215, v215, v16
	v_mul_f32_e32 v214, v214, v16
	v_mul_f32_e32 v205, v205, v16
	v_mul_f32_e32 v204, v204, v16
	v_mul_f32_e32 v203, v203, v16
	v_mul_f32_e32 v202, v202, v16
	v_mul_f32_e32 v201, v201, v16
	v_mul_f32_e32 v200, v200, v16
	v_mul_f32_e32 v198, v198, v16
	v_mul_f32_e32 v197, v197, v16
	v_mul_f32_e32 v196, v196, v16
	v_mul_f32_e32 v195, v195, v16
	v_mul_f32_e32 v194, v194, v16
	v_mul_f32_e32 v193, v193, v16
	v_mul_f32_e32 v192, v192, v16
	v_mul_f32_e32 v191, v191, v16
	s_waitcnt lgkmcnt(0)
	v_add_f32_e32 v215, v215, v22
	v_add_f32_e32 v214, v214, v23
	v_add_f32_e32 v205, v205, v24
	v_add_f32_e32 v204, v204, v25
	v_add_f32_e32 v203, v203, v26
	v_add_f32_e32 v202, v202, v27
	v_add_f32_e32 v201, v201, v28
	v_add_f32_e32 v200, v200, v29
	v_add_f32_e32 v198, v198, v30
	v_add_f32_e32 v197, v197, v31
	v_add_f32_e32 v196, v196, v32
	v_add_f32_e32 v195, v195, v33
	v_add_f32_e32 v194, v194, v34
	v_add_f32_e32 v193, v193, v35
	v_add_f32_e32 v192, v192, v36
	v_add_f32_e32 v191, v191, v37
	ds_write_b32 v117, v215
	ds_write_b32 v117, v214 offset:128
	ds_write_b32 v117, v205 offset:256
	ds_write_b32 v117, v204 offset:384
	ds_write_b32 v117, v203 offset:1024
	ds_write_b32 v117, v202 offset:1152
	ds_write_b32 v117, v201 offset:1280
	ds_write_b32 v117, v200 offset:1408
	ds_write_b32 v117, v198 offset:2048
	ds_write_b32 v117, v197 offset:2176
	ds_write_b32 v117, v196 offset:2304
	ds_write_b32 v117, v195 offset:2432
	ds_write_b32 v117, v194 offset:3072
	ds_write_b32 v117, v193 offset:3200
	ds_write_b32 v117, v192 offset:3328
	ds_write_b32 v117, v191 offset:3456
	ds_read_b32 v22, v117 offset:4096
	ds_read_b32 v23, v117 offset:4224
	ds_read_b32 v24, v117 offset:4352
	ds_read_b32 v25, v117 offset:4480
	ds_read_b32 v26, v117 offset:5120
	ds_read_b32 v27, v117 offset:5248
	ds_read_b32 v28, v117 offset:5376
	ds_read_b32 v29, v117 offset:5504
	ds_read_b32 v30, v117 offset:6144
	ds_read_b32 v31, v117 offset:6272
	ds_read_b32 v32, v117 offset:6400
	ds_read_b32 v33, v117 offset:6528
	ds_read_b32 v34, v117 offset:7168
	ds_read_b32 v35, v117 offset:7296
	ds_read_b32 v36, v117 offset:7424
	ds_read_b32 v37, v117 offset:7552
	v_mul_f32_e32 v219, v219, v16
	v_mul_f32_e32 v218, v218, v16
	v_mul_f32_e32 v217, v217, v16
	v_mul_f32_e32 v216, v216, v16
	v_mul_f32_e32 v59, v59, v16
	v_mul_f32_e32 v58, v58, v16
	v_mul_f32_e32 v57, v57, v16
	v_mul_f32_e32 v56, v56, v16
	v_mul_f32_e32 v55, v55, v16
	v_mul_f32_e32 v54, v54, v16
	v_mul_f32_e32 v53, v53, v16
	v_mul_f32_e32 v52, v52, v16
	v_mul_f32_e32 v51, v51, v16
	v_mul_f32_e32 v50, v50, v16
	v_mul_f32_e32 v49, v49, v16
	v_mul_f32_e32 v48, v48, v16
	s_waitcnt lgkmcnt(0)
	v_add_f32_e32 v219, v219, v22
	v_add_f32_e32 v218, v218, v23
	v_add_f32_e32 v217, v217, v24
	v_add_f32_e32 v216, v216, v25
	v_add_f32_e32 v59, v59, v26
	v_add_f32_e32 v58, v58, v27
	v_add_f32_e32 v57, v57, v28
	v_add_f32_e32 v56, v56, v29
	v_add_f32_e32 v55, v55, v30
	v_add_f32_e32 v54, v54, v31
	v_add_f32_e32 v53, v53, v32
	v_add_f32_e32 v52, v52, v33
	v_add_f32_e32 v51, v51, v34
	v_add_f32_e32 v50, v50, v35
	v_add_f32_e32 v49, v49, v36
	v_add_f32_e32 v48, v48, v37
	ds_write_b32 v117, v219 offset:4096
	ds_write_b32 v117, v218 offset:4224
	ds_write_b32 v117, v217 offset:4352
	ds_write_b32 v117, v216 offset:4480
	ds_write_b32 v117, v59 offset:5120
	ds_write_b32 v117, v58 offset:5248
	ds_write_b32 v117, v57 offset:5376
	ds_write_b32 v117, v56 offset:5504
	ds_write_b32 v117, v55 offset:6144
	ds_write_b32 v117, v54 offset:6272
	ds_write_b32 v117, v53 offset:6400
	ds_write_b32 v117, v52 offset:6528
	ds_write_b32 v117, v51 offset:7168
	ds_write_b32 v117, v50 offset:7296
	ds_write_b32 v117, v49 offset:7424
	ds_write_b32 v117, v48 offset:7552
	ds_read_b32 v22, v117 offset:8192
	ds_read_b32 v23, v117 offset:8320
	ds_read_b32 v24, v117 offset:8448
	ds_read_b32 v25, v117 offset:8576
	ds_read_b32 v26, v117 offset:9216
	ds_read_b32 v27, v117 offset:9344
	ds_read_b32 v28, v117 offset:9472
	ds_read_b32 v29, v117 offset:9600
	ds_read_b32 v30, v117 offset:10240
	ds_read_b32 v31, v117 offset:10368
	ds_read_b32 v32, v117 offset:10496
	ds_read_b32 v33, v117 offset:10624
	ds_read_b32 v34, v117 offset:11264
	ds_read_b32 v35, v117 offset:11392
	ds_read_b32 v36, v117 offset:11520
	ds_read_b32 v37, v117 offset:11648
	v_mul_f32_e32 v235, v235, v16
	v_mul_f32_e32 v234, v234, v16
	v_mul_f32_e32 v233, v233, v16
	v_mul_f32_e32 v232, v232, v16
	v_mul_f32_e32 v231, v231, v16
	v_mul_f32_e32 v230, v230, v16
	v_mul_f32_e32 v229, v229, v16
	v_mul_f32_e32 v228, v228, v16
	v_mul_f32_e32 v227, v227, v16
	v_mul_f32_e32 v226, v226, v16
	v_mul_f32_e32 v225, v225, v16
	v_mul_f32_e32 v224, v224, v16
	v_mul_f32_e32 v223, v223, v16
	v_mul_f32_e32 v222, v222, v16
	v_mul_f32_e32 v221, v221, v16
	v_mul_f32_e32 v220, v220, v16
	s_waitcnt lgkmcnt(0)
	v_add_f32_e32 v235, v235, v22
	v_add_f32_e32 v234, v234, v23
	v_add_f32_e32 v233, v233, v24
	v_add_f32_e32 v232, v232, v25
	v_add_f32_e32 v231, v231, v26
	v_add_f32_e32 v230, v230, v27
	v_add_f32_e32 v229, v229, v28
	v_add_f32_e32 v228, v228, v29
	v_add_f32_e32 v227, v227, v30
	v_add_f32_e32 v226, v226, v31
	v_add_f32_e32 v225, v225, v32
	v_add_f32_e32 v224, v224, v33
	v_add_f32_e32 v223, v223, v34
	v_add_f32_e32 v222, v222, v35
	v_add_f32_e32 v221, v221, v36
	v_add_f32_e32 v220, v220, v37
	ds_write_b32 v117, v235 offset:8192
	ds_write_b32 v117, v234 offset:8320
	ds_write_b32 v117, v233 offset:8448
	ds_write_b32 v117, v232 offset:8576
	ds_write_b32 v117, v231 offset:9216
	ds_write_b32 v117, v230 offset:9344
	ds_write_b32 v117, v229 offset:9472
	ds_write_b32 v117, v228 offset:9600
	ds_write_b32 v117, v227 offset:10240
	ds_write_b32 v117, v226 offset:10368
	ds_write_b32 v117, v225 offset:10496
	ds_write_b32 v117, v224 offset:10624
	ds_write_b32 v117, v223 offset:11264
	ds_write_b32 v117, v222 offset:11392
	ds_write_b32 v117, v221 offset:11520
	ds_write_b32 v117, v220 offset:11648
	ds_read_b32 v22, v117 offset:12288
	ds_read_b32 v23, v117 offset:12416
	ds_read_b32 v24, v117 offset:12544
	ds_read_b32 v25, v117 offset:12672
	ds_read_b32 v26, v117 offset:13312
	ds_read_b32 v27, v117 offset:13440
	ds_read_b32 v28, v117 offset:13568
	ds_read_b32 v29, v117 offset:13696
	ds_read_b32 v30, v117 offset:14336
	ds_read_b32 v31, v117 offset:14464
	ds_read_b32 v32, v117 offset:14592
	ds_read_b32 v33, v117 offset:14720
	ds_read_b32 v34, v117 offset:15360
	ds_read_b32 v35, v117 offset:15488
	ds_read_b32 v36, v117 offset:15616
	ds_read_b32 v37, v117 offset:15744
	v_mul_f32_e32 v0, v0, v16
	v_mul_f32_e32 v1, v1, v16
	v_mul_f32_e32 v2, v2, v16
	v_mul_f32_e32 v3, v3, v16
	v_mul_f32_e32 v4, v4, v16
	v_mul_f32_e32 v5, v5, v16
	v_mul_f32_e32 v6, v6, v16
	v_mul_f32_e32 v7, v7, v16
	v_mul_f32_e32 v8, v8, v16
	v_mul_f32_e32 v9, v9, v16
	v_mul_f32_e32 v10, v10, v16
	v_mul_f32_e32 v11, v11, v16
	v_mul_f32_e32 v12, v12, v16
	v_mul_f32_e32 v13, v13, v16
	v_mul_f32_e32 v14, v14, v16
	v_mul_f32_e32 v15, v15, v16
	s_waitcnt lgkmcnt(0)
	v_add_f32_e32 v0, v0, v22
	v_add_f32_e32 v1, v1, v23
	v_add_f32_e32 v2, v2, v24
	v_add_f32_e32 v3, v3, v25
	v_add_f32_e32 v4, v4, v26
	v_add_f32_e32 v5, v5, v27
	v_add_f32_e32 v6, v6, v28
	v_add_f32_e32 v7, v7, v29
	v_add_f32_e32 v8, v8, v30
	v_add_f32_e32 v9, v9, v31
	v_add_f32_e32 v10, v10, v32
	v_add_f32_e32 v11, v11, v33
	v_add_f32_e32 v12, v12, v34
	v_add_f32_e32 v13, v13, v35
	v_add_f32_e32 v14, v14, v36
	v_add_f32_e32 v15, v15, v37
	ds_write_b32 v117, v0 offset:12288
	ds_write_b32 v117, v1 offset:12416
	ds_write_b32 v117, v2 offset:12544
	ds_write_b32 v117, v3 offset:12672
	ds_write_b32 v117, v4 offset:13312
	ds_write_b32 v117, v5 offset:13440
	ds_write_b32 v117, v6 offset:13568
	ds_write_b32 v117, v7 offset:13696
	ds_write_b32 v117, v8 offset:14336
	ds_write_b32 v117, v9 offset:14464
	ds_write_b32 v117, v10 offset:14592
	ds_write_b32 v117, v11 offset:14720
	ds_write_b32 v117, v12 offset:15360
	ds_write_b32 v117, v13 offset:15488
	ds_write_b32 v117, v14 offset:15616
	ds_write_b32 v117, v15 offset:15744
	s_branch .LBB0_851
.Lmy_ps_first:
	v_mul_f32_e32 v215, v215, v16
	v_mul_f32_e32 v214, v214, v16
	v_mul_f32_e32 v205, v205, v16
	v_mul_f32_e32 v204, v204, v16
	v_mul_f32_e32 v203, v203, v16
	v_mul_f32_e32 v202, v202, v16
	v_mul_f32_e32 v201, v201, v16
	v_mul_f32_e32 v200, v200, v16
	v_mul_f32_e32 v198, v198, v16
	v_mul_f32_e32 v197, v197, v16
	v_mul_f32_e32 v196, v196, v16
	v_mul_f32_e32 v195, v195, v16
	v_mul_f32_e32 v194, v194, v16
	v_mul_f32_e32 v193, v193, v16
	v_mul_f32_e32 v192, v192, v16
	v_mul_f32_e32 v191, v191, v16
	v_mul_f32_e32 v219, v219, v16
	v_mul_f32_e32 v218, v218, v16
	v_mul_f32_e32 v217, v217, v16
	v_mul_f32_e32 v216, v216, v16
	v_mul_f32_e32 v59, v59, v16
	v_mul_f32_e32 v58, v58, v16
	v_mul_f32_e32 v57, v57, v16
	v_mul_f32_e32 v56, v56, v16
	v_mul_f32_e32 v55, v55, v16
	v_mul_f32_e32 v54, v54, v16
	v_mul_f32_e32 v53, v53, v16
	v_mul_f32_e32 v52, v52, v16
	v_mul_f32_e32 v51, v51, v16
	v_mul_f32_e32 v50, v50, v16
	v_mul_f32_e32 v49, v49, v16
	v_mul_f32_e32 v48, v48, v16
	v_mul_f32_e32 v235, v235, v16
	v_mul_f32_e32 v234, v234, v16
	v_mul_f32_e32 v233, v233, v16
	v_mul_f32_e32 v232, v232, v16
	v_mul_f32_e32 v231, v231, v16
	v_mul_f32_e32 v230, v230, v16
	v_mul_f32_e32 v229, v229, v16
	v_mul_f32_e32 v228, v228, v16
	v_mul_f32_e32 v227, v227, v16
	v_mul_f32_e32 v226, v226, v16
	v_mul_f32_e32 v225, v225, v16
	v_mul_f32_e32 v224, v224, v16
	v_mul_f32_e32 v223, v223, v16
	v_mul_f32_e32 v222, v222, v16
	v_mul_f32_e32 v221, v221, v16
	v_mul_f32_e32 v220, v220, v16
	v_mul_f32_e32 v0, v0, v16
	v_mul_f32_e32 v1, v1, v16
	v_mul_f32_e32 v2, v2, v16
	v_mul_f32_e32 v3, v3, v16
	v_mul_f32_e32 v4, v4, v16
	v_mul_f32_e32 v5, v5, v16
	v_mul_f32_e32 v6, v6, v16
	v_mul_f32_e32 v7, v7, v16
	v_mul_f32_e32 v8, v8, v16
	v_mul_f32_e32 v9, v9, v16
	v_mul_f32_e32 v10, v10, v16
	v_mul_f32_e32 v11, v11, v16
	v_mul_f32_e32 v12, v12, v16
	v_mul_f32_e32 v13, v13, v16
	v_mul_f32_e32 v14, v14, v16
	v_mul_f32_e32 v15, v15, v16
	ds_write_b32 v117, v215
	ds_write_b32 v117, v214 offset:128
	ds_write_b32 v117, v205 offset:256
	ds_write_b32 v117, v204 offset:384
	ds_write_b32 v117, v203 offset:1024
	ds_write_b32 v117, v202 offset:1152
	ds_write_b32 v117, v201 offset:1280
	ds_write_b32 v117, v200 offset:1408
	ds_write_b32 v117, v198 offset:2048
	ds_write_b32 v117, v197 offset:2176
	ds_write_b32 v117, v196 offset:2304
	ds_write_b32 v117, v195 offset:2432
	ds_write_b32 v117, v194 offset:3072
	ds_write_b32 v117, v193 offset:3200
	ds_write_b32 v117, v192 offset:3328
	ds_write_b32 v117, v191 offset:3456
	ds_write_b32 v117, v219 offset:4096
	ds_write_b32 v117, v218 offset:4224
	ds_write_b32 v117, v217 offset:4352
	ds_write_b32 v117, v216 offset:4480
	ds_write_b32 v117, v59 offset:5120
	ds_write_b32 v117, v58 offset:5248
	ds_write_b32 v117, v57 offset:5376
	ds_write_b32 v117, v56 offset:5504
	ds_write_b32 v117, v55 offset:6144
	ds_write_b32 v117, v54 offset:6272
	ds_write_b32 v117, v53 offset:6400
	ds_write_b32 v117, v52 offset:6528
	ds_write_b32 v117, v51 offset:7168
	ds_write_b32 v117, v50 offset:7296
	ds_write_b32 v117, v49 offset:7424
	ds_write_b32 v117, v48 offset:7552
	ds_write_b32 v117, v235 offset:8192
	ds_write_b32 v117, v234 offset:8320
	ds_write_b32 v117, v233 offset:8448
	ds_write_b32 v117, v232 offset:8576
	ds_write_b32 v117, v231 offset:9216
	ds_write_b32 v117, v230 offset:9344
	ds_write_b32 v117, v229 offset:9472
	ds_write_b32 v117, v228 offset:9600
	ds_write_b32 v117, v227 offset:10240
	ds_write_b32 v117, v226 offset:10368
	ds_write_b32 v117, v225 offset:10496
	ds_write_b32 v117, v224 offset:10624
	ds_write_b32 v117, v223 offset:11264
	ds_write_b32 v117, v222 offset:11392
	ds_write_b32 v117, v221 offset:11520
	ds_write_b32 v117, v220 offset:11648
	ds_write_b32 v117, v0 offset:12288
	ds_write_b32 v117, v1 offset:12416
	ds_write_b32 v117, v2 offset:12544
	ds_write_b32 v117, v3 offset:12672
	ds_write_b32 v117, v4 offset:13312
	ds_write_b32 v117, v5 offset:13440
	ds_write_b32 v117, v6 offset:13568
	ds_write_b32 v117, v7 offset:13696
	ds_write_b32 v117, v8 offset:14336
	ds_write_b32 v117, v9 offset:14464
	ds_write_b32 v117, v10 offset:14592
	ds_write_b32 v117, v11 offset:14720
	ds_write_b32 v117, v12 offset:15360
	ds_write_b32 v117, v13 offset:15488
	ds_write_b32 v117, v14 offset:15616
	ds_write_b32 v117, v15 offset:15744
	s_branch .LBB0_851
